# panel-group barrier spin re-polls without the s_sleep (loop-edge edit on the serial wait chain)
# speedup vs baseline: 1.0078x; 1.0078x over previous
.Lxb4_gspin:
	global_load_dword v8, v4, s[34:35] sc1
	s_waitcnt vmcnt(0)
	v_cmp_lt_u32_e32 vcc, 3, v8
	s_cbranch_vccnz .Lxb4_acq
	s_add_i32 s42, s42, 1
	s_cmp_lt_u32 s42, 0x400000
	s_cbranch_scc0 .Lxb4_acq
	s_branch .Lxb4_gspin
